# kt-MFMA version + nt (streaming) hint on the GDN scan operand loads
# baseline (speedup 1.0000x reference)
; #define LAS __attribute__((address_space(3)))
; DI int TID() { int t = __builtin_amdgcn_workitem_id_x(); asm volatile("" : "+v"(t)); return t; }
; DI void lds_barrier() { asm volatile("s_waitcnt lgkmcnt(0)" ::: "memory"); __builtin_amdgcn_s_barrier(); asm volatile("" ::: "memory"); }
; DI void gdn_scan(LAS unsigned char* lds, PP p, int wg) {
;     const int tid = TID(), w = tid >> 6, lane = tid & 63, r = lane & 31, h = lane >> 5;
;     const int hd = wg & 7, cb = wg >> 3, rt = w & 3; const bool act = w < 4;
;     LAS u32x4* Simg = (LAS u32x4*)lds;
;     LAS u32x4* Vimg = (LAS u32x4*)(lds + 8192);
;     LAS bf16_t* Oimg = (LAS bf16_t*)(lds + 12288);
;     f32x16 S; for (int i = 0; i < 16; ++i) S[i] = 0.f;
;     if (act) { Simg[(2 * rt) * 64 + lane] = (u32x4){0u, 0u, 0u, 0u}; Simg[(2 * rt + 1) * 64 + lane] = (u32x4){0u, 0u, 0u, 0u}; }
;     lds_barrier();
;     const unsigned char* fb = p->ws + O_A + (size_t)(hd * 256) * FRAG_ITEM;
;     const unsigned char* ub = p->ws + O_UFR + (size_t)(hd * 256) * UFR_ITEM;
;     const float* GL = (const float*)(p->ws + O_GL) + hd * 256;
;     bf16_t* obf = (bf16_t*)(p->ws + O_OBF);
;     const size_t a1off = (rt < 2 ? 0 : 16384) + (size_t)((rt & 1) * 8) * 1024 + lane * 16;
;     const size_t ktoff = 40960 + (size_t)(rt * 4) * 1024 + lane * 16;
;     const unsigned char* xbase = rt >= 2 ? fb + 32768 + (size_t)((rt & 1) * 4) * 1024 + lane * 16 : ub + (size_t)((rt & 1) * 4 + cb) * 4096 + lane * 16;
;     const size_t xitem = rt >= 2 ? FRAG_ITEM : UFR_ITEM;
.LBB0_355:
	s_or_b64 exec, exec, s[2:3]
	s_and_b32 s30, s63, 7
	s_ashr_i32 s31, s63, 3
	s_lshl_b32 s34, s30, 8
	s_mul_i32 s2, s30, 0xe00000
	s_add_u32 s2, s94, s2
	s_waitcnt lgkmcnt(0)
	s_barrier
	s_addc_u32 s3, s95, 0
	s_add_u32 s20, s2, 0xb100000
	s_addc_u32 s21, s3, 0
	v_bfe_u32 v7, v4, 6, 1
	v_cmp_lt_u32_e64 s[24:25], 1, v5
	v_cmp_gt_u32_e64 s[26:27], 2, v5
	s_and_saveexec_b64 s[2:3], s[26:27]
	s_xor_b64 s[2:3], exec, s[2:3]
	s_lshl_b32 s28, s34, 15
	v_lshl_add_u32 v0, v7, 2, s31
	s_add_u32 s28, s94, s28
	v_ashrrev_i32_e32 v1, 31, v0
	s_addc_u32 s29, s95, 0
	v_lshlrev_b64 v[0:1], 12, v[0:1]
	v_lshl_add_u64 v[0:1], s[28:29], 0, v[0:1]
	s_mov_b64 s[28:29], 0x12100000
	v_lshl_add_u64 v[0:1], v[0:1], 0, s[28:29]
	s_or_saveexec_b64 s[2:3], s[2:3]
	v_mov_b64_e32 v[202:203], 0x8000
	s_xor_b64 exec, exec, s[2:3]
	v_lshlrev_b32_e32 v0, 12, v7
	v_mov_b32_e32 v1, v3
	v_lshl_add_u64 v[0:1], s[20:21], 0, v[0:1]
	s_mov_b64 s[28:29], 0x8000
	v_lshl_add_u64 v[0:1], v[0:1], 0, s[28:29]
	v_mov_b64_e32 v[202:203], 0xe000
	s_or_b64 exec, exec, s[2:3]
	s_lshl_b32 s2, s34, 2
	s_add_u32 s38, s94, s2
	s_addc_u32 s39, s95, 0
	v_lshl_add_u64 v[204:205], v[0:1], 0, v[2:3]
	v_lshlrev_b32_e32 v0, 2, v6
	v_mov_b32_e32 v1, v3
	v_lshl_add_u64 v[0:1], s[38:39], 0, v[0:1]
	s_mov_b64 s[38:39], 0x2da20000
	s_mov_b32 s35, 0x2da20000
	v_lshl_add_u64 v[12:13], v[0:1], 0, s[38:39]
	v_add_co_u32_e32 v0, vcc, s35, v0
	v_cmp_gt_u32_e64 s[28:29], 2, v5
	s_nop 0
	v_addc_co_u32_e32 v1, vcc, 0, v1, vcc
	global_load_dword v231, v[0:1], off
	global_load_dword v232, v[12:13], off offset:256
	global_load_dword v233, v[12:13], off offset:512
	global_load_dword v234, v[12:13], off offset:768
	v_mov_b32_e32 v8, 0x4000
	v_cndmask_b32_e64 v8, v8, 0, s[28:29]
	v_lshlrev_b32_e32 v7, 13, v7
	v_or3_b32 v8, v7, v2, v8
	v_mov_b32_e32 v9, v3
	s_waitcnt vmcnt(0)
; #define TIE8(NSTR, a, b) asm volatile("s_waitcnt vmcnt(" NSTR ")" : "+v"(a[0]), "+v"(a[1]), "+v"(a[2]), "+v"(a[3]), "+v"(b[0]), "+v"(b[1]), "+v"(b[2]), "+v"(b[3]) :: "memory")
; #define SCAN_LOAD_A1(A1_, n_) do { const unsigned char* f_ = fb + (size_t)(n_) * FRAG_ITEM + a1off; \
;         _Pragma("unroll") for (int s = 0; s < 8; ++s) GLD16(A1_[s], f_ + s * 1024); } while (0)
; #define SCAN_LOAD_X(KT_, X_, n_) do { const unsigned char* f_ = fb + (size_t)(n_) * FRAG_ITEM + ktoff; const unsigned char* x_ = xbase + (size_t)(n_) * xitem; \
;         _Pragma("unroll") for (int s = 0; s < 4; ++s) GLD16(KT_[s], f_ + s * 1024); \
;         _Pragma("unroll") for (int s = 0; s < 4; ++s) GLD16(X_[s], x_ + s * 1024); } while (0)
; DI void gdn_scan(LAS unsigned char* lds, PP p, int wg) {
;     ...
;     u32x4 A1a[8], A1b[8], KTa[4], KTb[4], Xa[4], Xb[4];
;     const float glr0 = GL[lane], glr1 = GL[64 + lane], glr2 = GL[128 + lane], glr3 = GL[192 + lane];
;     asm volatile("s_waitcnt vmcnt(0)" ::: "memory");
;     SCAN_LOAD_A1(A1a, 0); SCAN_LOAD_X(KTa, Xa, 0); SCAN_LOAD_A1(A1b, 1); SCAN_LOAD_X(KTb, Xb, 1);
;     TIE8("0", A1a, (A1a + 4)); TIE8("0", KTa, Xa); TIE8("0", A1b, (A1b + 4)); TIE8("0", KTb, Xb);
	v_lshl_add_u64 v[206:207], s[20:21], 0, v[8:9]
	global_load_dwordx4 v[72:75], v[206:207], off nt
	s_mov_b64 s[50:51], 0x400
	v_lshl_add_u64 v[0:1], v[206:207], 0, s[50:51]
	global_load_dwordx4 v[68:71], v[0:1], off nt
	s_mov_b64 s[52:53], 0x800
	v_lshl_add_u64 v[0:1], v[206:207], 0, s[52:53]
	global_load_dwordx4 v[88:91], v[0:1], off nt
	s_mov_b64 s[54:55], 0xc00
	v_lshl_add_u64 v[0:1], v[206:207], 0, s[54:55]
	global_load_dwordx4 v[84:87], v[0:1], off nt
	s_mov_b64 s[38:39], 0x1000
	v_lshl_add_u64 v[0:1], v[206:207], 0, s[38:39]
	global_load_dwordx4 v[100:103], v[0:1], off nt
	s_mov_b64 s[44:45], 0x1400
	v_lshl_add_u64 v[0:1], v[206:207], 0, s[44:45]
	global_load_dwordx4 v[92:95], v[0:1], off nt
	s_mov_b64 s[40:41], 0x1800
	v_lshl_or_b32 v7, v5, 12, v2
	v_lshl_add_u64 v[0:1], v[206:207], 0, s[40:41]
	global_load_dwordx4 v[152:155], v[0:1], off nt
	s_mov_b64 s[48:49], 0x1c00
	v_add_u32_e32 v10, 0xa000, v7
	v_mov_b32_e32 v11, v3
	v_lshl_add_u64 v[0:1], v[206:207], 0, s[48:49]
	global_load_dwordx4 v[144:147], v[0:1], off nt
	v_lshl_add_u64 v[208:209], s[20:21], 0, v[10:11]
	global_load_dwordx4 v[112:115], v[208:209], off nt
	v_lshl_add_u64 v[0:1], v[208:209], 0, s[50:51]
	global_load_dwordx4 v[104:107], v[0:1], off nt
	v_lshl_add_u64 v[0:1], v[208:209], 0, s[52:53]
	global_load_dwordx4 v[80:83], v[0:1], off nt
	v_lshl_add_u64 v[0:1], v[208:209], 0, s[54:55]
	global_load_dwordx4 v[64:67], v[0:1], off nt
	s_add_u32 s2, s94, 0x28100000
	global_load_dwordx4 v[120:123], v[204:205], off nt
	s_addc_u32 s3, s95, 0
	v_lshl_add_u64 v[0:1], v[204:205], 0, s[50:51]
	global_load_dwordx4 v[108:111], v[0:1], off nt
	v_lshl_add_u64 v[0:1], v[204:205], 0, s[52:53]
	global_load_dwordx4 v[96:99], v[0:1], off nt
	s_add_u32 s20, s20, 0xe000
	v_lshl_add_u64 v[0:1], v[204:205], 0, s[54:55]
	global_load_dwordx4 v[76:79], v[0:1], off nt
	s_addc_u32 s21, s21, 0
	v_lshl_add_u64 v[0:1], s[20:21], 0, v[8:9]
	global_load_dwordx4 v[128:131], v[0:1], off nt
	v_lshl_add_u64 v[8:9], v[0:1], 0, s[50:51]
	global_load_dwordx4 v[124:127], v[8:9], off nt
	v_lshl_add_u64 v[8:9], v[0:1], 0, s[52:53]
	global_load_dwordx4 v[148:151], v[8:9], off nt
	v_lshl_add_u64 v[8:9], v[0:1], 0, s[54:55]
	global_load_dwordx4 v[132:135], v[8:9], off nt
	v_lshl_add_u64 v[8:9], v[0:1], 0, s[38:39]
	global_load_dwordx4 v[160:163], v[8:9], off nt
	v_lshl_add_u64 v[8:9], v[0:1], 0, s[44:45]
	global_load_dwordx4 v[156:159], v[8:9], off nt
	v_lshl_add_u64 v[8:9], v[0:1], 0, s[40:41]
	global_load_dwordx4 v[188:191], v[8:9], off nt
	v_lshl_add_u64 v[0:1], v[0:1], 0, s[48:49]
	global_load_dwordx4 v[184:187], v[0:1], off nt
	v_lshl_add_u64 v[0:1], s[20:21], 0, v[10:11]
	global_load_dwordx4 v[176:179], v[0:1], off nt
	v_lshl_add_u64 v[10:11], v[0:1], 0, s[50:51]
	global_load_dwordx4 v[168:171], v[10:11], off nt
	v_lshl_add_u64 v[10:11], v[0:1], 0, s[52:53]
	global_load_dwordx4 v[136:139], v[10:11], off nt
	v_lshl_add_u64 v[8:9], v[204:205], 0, v[202:203]
	v_lshl_add_u64 v[0:1], v[0:1], 0, s[54:55]
	global_load_dwordx4 v[116:119], v[0:1], off nt
	global_load_dwordx4 v[180:183], v[8:9], off nt
	v_lshl_add_u64 v[0:1], v[8:9], 0, s[50:51]
	global_load_dwordx4 v[172:175], v[0:1], off nt
	v_lshl_add_u64 v[0:1], v[8:9], 0, s[52:53]
	global_load_dwordx4 v[164:167], v[0:1], off nt
	v_lshl_add_u64 v[0:1], v[8:9], 0, s[54:55]
	global_load_dwordx4 v[140:143], v[0:1], off nt
	v_add_u32_e32 v0, -2, v5
	s_movk_i32 s20, 0xa00
	s_add_u32 s34, s2, s34
	v_add_u32_e32 v203, 0, v2
	v_mad_i32_i24 v0, v0, s20, 0
	v_lshlrev_b32_e32 v2, 4, v4
	s_addc_u32 s35, s3, 0
	s_lshl_b32 s20, s31, 5
	v_and_b32_e32 v7, 31, v4
	v_and_b32_e32 v2, 48, v2
	s_ashr_i32 s21, s20, 31
	v_lshl_add_u32 v235, v7, 1, v0
	v_add_u32_e32 v236, v0, v2
	s_lshl_b64 s[20:21], s[20:21], 1
	v_lshrrev_b32_e32 v0, 2, v6
	s_add_u32 s34, s34, s20
	v_mul_u32_u24_e32 v238, 0x50, v0
	v_lshl_or_b32 v5, v5, 5, v0
	v_and_b32_e32 v0, 3, v4
	v_lshrrev_b32_e32 v1, 3, v4
	s_addc_u32 s35, s35, s21
	v_lshlrev_b32_e32 v0, 4, v0
	s_waitcnt vmcnt(0)
	v_and_b32_e32 v1, 4, v1
	v_lshl_add_u64 v[210:211], s[34:35], 0, v[2:3]
	v_lshl_or_b32 v2, s30, 8, v0
	v_lshlrev_b32_e32 v6, 11, v5
	s_waitcnt vmcnt(0)
	v_mul_u32_u24_e32 v237, 0x50, v1
	v_subrev_u32_e32 v212, 64, v5
	v_lshl_add_u64 v[0:1], v[2:3], 0, s[20:21]
	v_or_b32_e32 v4, 0x8000, v6
	v_mov_b32_e32 v5, v3
	s_waitcnt vmcnt(0)
	v_lshl_add_u64 v[0:1], v[0:1], 0, v[4:5]
	s_waitcnt vmcnt(0)
	v_lshl_add_u64 v[214:215], s[2:3], 0, v[0:1]
	s_add_u32 s2, s2, s20
	v_mov_b32_e32 v30, v3
	v_mov_b32_e32 v31, v3
	v_or_b32_e32 v2, v2, v6
	s_addc_u32 s3, s3, s21
	v_mov_b32_e32 v16, v3
	v_mov_b32_e32 v17, v3
	v_mov_b32_e32 v18, v3
	v_mov_b32_e32 v19, v3
	v_mov_b32_e32 v20, v3
	v_mov_b32_e32 v21, v3
	v_mov_b32_e32 v22, v3
	v_mov_b32_e32 v23, v3
	v_mov_b32_e32 v24, v3
	v_mov_b32_e32 v25, v3
	v_mov_b32_e32 v26, v3
	v_mov_b32_e32 v27, v3
	v_mov_b32_e32 v28, v3
	v_mov_b32_e32 v29, v3
	v_mov_b64_e32 v[46:47], v[30:31]
	s_mov_b32 s37, 0
	s_mov_b64 s[42:43], 0x1000
	s_mov_b64 s[58:59], 0x1400
	s_mov_b64 s[44:45], 0x1800
	s_mov_b64 s[60:61], 0x1c00
	s_mov_b64 s[48:49], 0x400
	s_mov_b64 s[50:51], 0x800
	s_mov_b64 s[52:53], 0xc00
	v_lshl_add_u64 v[216:217], s[2:3], 0, v[2:3]
	v_mov_b64_e32 v[44:45], v[28:29]
	v_mov_b64_e32 v[42:43], v[26:27]
	v_mov_b64_e32 v[40:41], v[24:25]
	v_mov_b64_e32 v[38:39], v[22:23]
	v_mov_b64_e32 v[36:37], v[20:21]
	v_mov_b64_e32 v[34:35], v[18:19]
	v_mov_b64_e32 v[32:33], v[16:17]
	s_waitcnt vmcnt(0)
	s_branch .LBB0_362

.LBB0_367:
	s_or_b64 exec, exec, s[34:35]
	s_mul_i32 s56, s38, 0xe000
	s_waitcnt lgkmcnt(6)
	v_mfma_f32_32x32x16_bf16 v[48:63], v[72:75], v[4:7], 0
	ds_read_b128 v[4:7], v203 offset:7168
	s_waitcnt lgkmcnt(6)
	v_mfma_f32_32x32x16_bf16 v[48:63], v[68:71], v[8:11], v[48:63]
	s_waitcnt lgkmcnt(5)
	v_mfma_f32_32x32x16_bf16 v[48:63], v[88:91], v[12:15], v[48:63]
	s_waitcnt lgkmcnt(4)
	v_mfma_f32_32x32x16_bf16 v[48:63], v[84:87], v[16:19], v[48:63]
	s_waitcnt lgkmcnt(3)
	v_mfma_f32_32x32x16_bf16 v[48:63], v[100:103], v[20:23], v[48:63]
	s_waitcnt lgkmcnt(2)
	v_mfma_f32_32x32x16_bf16 v[48:63], v[92:95], v[24:27], v[48:63]
	s_waitcnt lgkmcnt(1)
	v_mfma_f32_32x32x16_bf16 v[48:63], v[152:155], v[28:31], v[48:63]
	s_waitcnt lgkmcnt(0)
	v_mfma_f32_32x32x16_bf16 v[48:63], v[144:147], v[4:7], v[48:63]
	v_lshl_add_u64 v[4:5], v[206:207], 0, s[56:57]
	global_load_dwordx4 v[72:75], v[4:5], off nt
	v_lshl_add_u64 v[6:7], v[4:5], 0, s[48:49]
	global_load_dwordx4 v[68:71], v[6:7], off nt
	v_lshl_add_u64 v[6:7], v[4:5], 0, s[50:51]
	global_load_dwordx4 v[88:91], v[6:7], off nt
	v_lshl_add_u64 v[6:7], v[4:5], 0, s[52:53]
	global_load_dwordx4 v[84:87], v[6:7], off nt
	v_lshl_add_u64 v[6:7], v[4:5], 0, s[42:43]
	global_load_dwordx4 v[100:103], v[6:7], off nt
	v_lshl_add_u64 v[6:7], v[4:5], 0, s[58:59]
	global_load_dwordx4 v[92:95], v[6:7], off nt
	v_lshl_add_u64 v[6:7], v[4:5], 0, s[44:45]
	global_load_dwordx4 v[152:155], v[6:7], off nt
	v_lshl_add_u64 v[4:5], v[4:5], 0, s[60:61]
	global_load_dwordx4 v[144:147], v[4:5], off nt
	s_and_saveexec_b64 s[34:35], s[26:27]
	s_xor_b64 s[34:35], exec, s[34:35]
	s_cbranch_execnz .LBB0_405
	s_andn2_saveexec_b64 s[34:35], s[34:35]
	s_cbranch_execnz .LBB0_406

.LBB0_372:
	s_or_b64 exec, exec, s[30:31]
	s_waitcnt lgkmcnt(0)
	s_barrier
	s_and_saveexec_b64 s[30:31], s[22:23]
	s_cbranch_execz .LBB0_384
	ds_read_b128 v[4:7], v203 offset:8192
	ds_read_b128 v[8:11], v203 offset:9216
	ds_read_b128 v[12:15], v203 offset:10240
	ds_read_b128 v[16:19], v203 offset:11264
	v_pk_mul_f32 v[46:47], v[46:47], s[2:3] op_sel_hi:[1,0]
	v_pk_mul_f32 v[44:45], v[44:45], s[2:3] op_sel_hi:[1,0]
	v_pk_mul_f32 v[42:43], v[42:43], s[2:3] op_sel_hi:[1,0]
	v_pk_mul_f32 v[40:41], v[40:41], s[2:3] op_sel_hi:[1,0]
	v_pk_mul_f32 v[38:39], v[38:39], s[2:3] op_sel_hi:[1,0]
	v_pk_mul_f32 v[36:37], v[36:37], s[2:3] op_sel_hi:[1,0]
	v_pk_mul_f32 v[34:35], v[34:35], s[2:3] op_sel_hi:[1,0]
	v_pk_mul_f32 v[32:33], v[32:33], s[2:3] op_sel_hi:[1,0]
	s_waitcnt lgkmcnt(3)
	s_nop 0
	v_mfma_f32_32x32x16_bf16 v[32:47], v[112:115], v[4:7], v[32:47]
	s_and_saveexec_b64 s[2:3], s[24:25]
	v_mfma_f32_32x32x16_bf16 v[48:63], v[120:123], v[4:7], v[48:63]
	s_or_b64 exec, exec, s[2:3]
	s_waitcnt lgkmcnt(2)
	v_mfma_f32_32x32x16_bf16 v[32:47], v[104:107], v[8:11], v[32:47]
	s_and_saveexec_b64 s[2:3], s[24:25]
	v_mfma_f32_32x32x16_bf16 v[48:63], v[108:111], v[8:11], v[48:63]
	s_or_b64 exec, exec, s[2:3]
	s_waitcnt lgkmcnt(1)
	v_mfma_f32_32x32x16_bf16 v[32:47], v[80:83], v[12:15], v[32:47]
	s_and_saveexec_b64 s[2:3], s[24:25]
	v_mfma_f32_32x32x16_bf16 v[48:63], v[96:99], v[12:15], v[48:63]
	s_or_b64 exec, exec, s[2:3]
	s_waitcnt lgkmcnt(0)
	v_mfma_f32_32x32x16_bf16 v[32:47], v[64:67], v[16:19], v[32:47]
	s_and_saveexec_b64 s[2:3], s[24:25]
	v_mfma_f32_32x32x16_bf16 v[48:63], v[76:79], v[16:19], v[48:63]
	s_or_b64 exec, exec, s[2:3]
	v_mov_b32_e32 v1, 0xe000
	v_mad_u64_u32 v[4:5], s[2:3], s38, v1, v[208:209]
	v_mad_u64_u32 v[6:7], s[2:3], v202, s38, v[204:205]
	global_load_dwordx4 v[112:115], v[4:5], off nt
	s_mov_b64 s[2:3], 0x400
	s_nop 0
	v_lshl_add_u64 v[8:9], v[4:5], 0, s[2:3]
	global_load_dwordx4 v[104:107], v[8:9], off nt
	s_mov_b64 s[34:35], 0x800
	v_lshl_add_u64 v[8:9], v[4:5], 0, s[34:35]
	global_load_dwordx4 v[80:83], v[8:9], off nt
	s_mov_b64 s[38:39], 0xc00
	v_lshl_add_u64 v[4:5], v[4:5], 0, s[38:39]
	global_load_dwordx4 v[64:67], v[4:5], off nt
	global_load_dwordx4 v[120:123], v[6:7], off nt
	v_lshl_add_u64 v[4:5], v[6:7], 0, s[2:3]
	global_load_dwordx4 v[108:111], v[4:5], off nt
	v_lshl_add_u64 v[4:5], v[6:7], 0, s[34:35]
	global_load_dwordx4 v[96:99], v[4:5], off nt
	v_lshl_add_u64 v[4:5], v[6:7], 0, s[38:39]
	global_load_dwordx4 v[76:79], v[4:5], off nt
	s_mov_b64 s[48:49], 0x400
	s_mov_b64 s[50:51], 0x800
	s_mov_b64 s[52:53], 0xc00
	s_and_saveexec_b64 s[2:3], s[24:25]
	s_cbranch_execz .LBB0_383
	v_cvt_pk_bf16_f32 v1, v48, s0
	v_add_u32_e32 v2, v235, v237
	ds_write_b16 v2, v1 offset:12288
	v_cvt_pk_bf16_f32 v1, v49, s0
	ds_write_b16 v2, v1 offset:12368
	v_cvt_pk_bf16_f32 v1, v50, s0
	ds_write_b16 v2, v1 offset:12448
	v_cvt_pk_bf16_f32 v1, v51, s0
	ds_write_b16 v2, v1 offset:12528
	v_cvt_pk_bf16_f32 v1, v52, s0
	ds_write_b16 v2, v1 offset:12928
	v_cvt_pk_bf16_f32 v1, v53, s0
	ds_write_b16 v2, v1 offset:13008
	v_cvt_pk_bf16_f32 v1, v54, s0
	ds_write_b16 v2, v1 offset:13088
	v_cvt_pk_bf16_f32 v1, v55, s0
	ds_write_b16 v2, v1 offset:13168
	v_cvt_pk_bf16_f32 v1, v56, s0
	ds_write_b16 v2, v1 offset:13568
	v_cvt_pk_bf16_f32 v1, v57, s0
	ds_write_b16 v2, v1 offset:13648
	v_cvt_pk_bf16_f32 v1, v58, s0
	ds_write_b16 v2, v1 offset:13728
	v_cvt_pk_bf16_f32 v1, v59, s0
	ds_write_b16 v2, v1 offset:13808
	v_cvt_pk_bf16_f32 v1, v60, s0
	ds_write_b16 v2, v1 offset:14208
	v_cvt_pk_bf16_f32 v1, v61, s0
	ds_write_b16 v2, v1 offset:14288
	v_cvt_pk_bf16_f32 v1, v62, s0
	ds_write_b16 v2, v1 offset:14368
	v_cvt_pk_bf16_f32 v1, v63, s0
	ds_write_b16 v2, v1 offset:14448
	v_add_u32_e32 v1, v236, v238
	ds_read_b128 v[4:7], v1 offset:12288
	v_mov_b32_e32 v213, v3
	v_lshlrev_b64 v[8:9], 11, v[212:213]
	v_lshl_add_u64 v[12:13], v[210:211], 0, v[8:9]
	ds_read_b128 v[8:11], v1 offset:13568
	v_add_u32_e32 v2, 16, v212
	s_waitcnt lgkmcnt(1)
	global_store_dwordx4 v[12:13], v[4:7], off
	s_nop 1
	v_lshlrev_b64 v[4:5], 11, v[2:3]
	v_lshl_add_u64 v[4:5], v[210:211], 0, v[4:5]
	s_waitcnt lgkmcnt(0)
	global_store_dwordx4 v[4:5], v[8:11], off

.LBB0_389:
	s_or_b64 exec, exec, s[34:35]
	v_lshl_add_u64 v[0:1], v[206:207], 0, s[56:57]
	s_waitcnt lgkmcnt(6)
	v_mfma_f32_32x32x16_bf16 v[48:63], v[128:131], v[4:7], 0
	ds_read_b128 v[4:7], v203 offset:7168
	s_waitcnt lgkmcnt(6)
	v_mfma_f32_32x32x16_bf16 v[48:63], v[124:127], v[8:11], v[48:63]
	s_waitcnt lgkmcnt(5)
	v_mfma_f32_32x32x16_bf16 v[48:63], v[148:151], v[12:15], v[48:63]
	s_waitcnt lgkmcnt(4)
	v_mfma_f32_32x32x16_bf16 v[48:63], v[132:135], v[16:19], v[48:63]
	s_waitcnt lgkmcnt(3)
	v_mfma_f32_32x32x16_bf16 v[48:63], v[160:163], v[20:23], v[48:63]
	s_waitcnt lgkmcnt(2)
	v_mfma_f32_32x32x16_bf16 v[48:63], v[156:159], v[24:27], v[48:63]
	s_waitcnt lgkmcnt(1)
	v_mfma_f32_32x32x16_bf16 v[48:63], v[188:191], v[28:31], v[48:63]
	s_waitcnt lgkmcnt(0)
	v_mfma_f32_32x32x16_bf16 v[48:63], v[184:187], v[4:7], v[48:63]
	global_load_dwordx4 v[128:131], v[0:1], off nt
	v_lshl_add_u64 v[4:5], v[0:1], 0, s[48:49]
	global_load_dwordx4 v[124:127], v[4:5], off nt
	v_lshl_add_u64 v[4:5], v[0:1], 0, s[50:51]
	global_load_dwordx4 v[148:151], v[4:5], off nt
	v_lshl_add_u64 v[4:5], v[0:1], 0, s[52:53]
	global_load_dwordx4 v[132:135], v[4:5], off nt
	v_lshl_add_u64 v[4:5], v[0:1], 0, s[42:43]
	global_load_dwordx4 v[160:163], v[4:5], off nt
	v_lshl_add_u64 v[4:5], v[0:1], 0, s[58:59]
	global_load_dwordx4 v[156:159], v[4:5], off nt
	v_lshl_add_u64 v[4:5], v[0:1], 0, s[44:45]
	global_load_dwordx4 v[188:191], v[4:5], off nt
	v_lshl_add_u64 v[0:1], v[0:1], 0, s[60:61]
	global_load_dwordx4 v[184:187], v[0:1], off nt
	s_and_saveexec_b64 s[34:35], s[26:27]
	s_xor_b64 s[34:35], exec, s[34:35]
	s_cbranch_execnz .LBB0_407
	s_andn2_saveexec_b64 s[34:35], s[34:35]
	s_cbranch_execnz .LBB0_408

.LBB0_394:
	s_or_b64 exec, exec, s[30:31]
	s_waitcnt lgkmcnt(0)
	s_barrier
	s_and_saveexec_b64 s[30:31], s[22:23]
	s_cbranch_execz .LBB0_361
	ds_read_b128 v[4:7], v203 offset:8192
	ds_read_b128 v[8:11], v203 offset:9216
	ds_read_b128 v[12:15], v203 offset:10240
	ds_read_b128 v[16:19], v203 offset:11264
	v_pk_mul_f32 v[46:47], v[46:47], s[2:3] op_sel_hi:[1,0]
	v_pk_mul_f32 v[44:45], v[44:45], s[2:3] op_sel_hi:[1,0]
	v_pk_mul_f32 v[42:43], v[42:43], s[2:3] op_sel_hi:[1,0]
	v_pk_mul_f32 v[40:41], v[40:41], s[2:3] op_sel_hi:[1,0]
	v_pk_mul_f32 v[38:39], v[38:39], s[2:3] op_sel_hi:[1,0]
	v_pk_mul_f32 v[36:37], v[36:37], s[2:3] op_sel_hi:[1,0]
	v_pk_mul_f32 v[34:35], v[34:35], s[2:3] op_sel_hi:[1,0]
	v_pk_mul_f32 v[32:33], v[32:33], s[2:3] op_sel_hi:[1,0]
	s_waitcnt lgkmcnt(3)
	s_nop 0
	v_mfma_f32_32x32x16_bf16 v[32:47], v[176:179], v[4:7], v[32:47]
	s_and_saveexec_b64 s[2:3], s[24:25]
	v_mfma_f32_32x32x16_bf16 v[48:63], v[180:183], v[4:7], v[48:63]
	s_or_b64 exec, exec, s[2:3]
	s_waitcnt lgkmcnt(2)
	v_mfma_f32_32x32x16_bf16 v[32:47], v[168:171], v[8:11], v[32:47]
	s_and_saveexec_b64 s[2:3], s[24:25]
	v_mfma_f32_32x32x16_bf16 v[48:63], v[172:175], v[8:11], v[48:63]
	s_or_b64 exec, exec, s[2:3]
	s_waitcnt lgkmcnt(1)
	v_mfma_f32_32x32x16_bf16 v[32:47], v[136:139], v[12:15], v[32:47]
	s_and_saveexec_b64 s[2:3], s[24:25]
	v_mfma_f32_32x32x16_bf16 v[48:63], v[164:167], v[12:15], v[48:63]
	s_or_b64 exec, exec, s[2:3]
	s_waitcnt lgkmcnt(0)
	v_mfma_f32_32x32x16_bf16 v[32:47], v[116:119], v[16:19], v[32:47]
	s_and_saveexec_b64 s[2:3], s[24:25]
	v_mfma_f32_32x32x16_bf16 v[48:63], v[140:143], v[16:19], v[48:63]
	s_or_b64 exec, exec, s[2:3]
	v_mad_u64_u32 v[4:5], s[2:3], v202, s37, v[204:205]
	v_lshl_add_u64 v[0:1], v[208:209], 0, s[56:57]
	global_load_dwordx4 v[176:179], v[0:1], off nt
	s_mov_b64 s[2:3], 0x400
	v_lshl_add_u64 v[6:7], v[0:1], 0, s[2:3]
	global_load_dwordx4 v[168:171], v[6:7], off nt
	s_mov_b64 s[34:35], 0x800
	v_lshl_add_u64 v[6:7], v[0:1], 0, s[34:35]
	global_load_dwordx4 v[136:139], v[6:7], off nt
	s_mov_b64 s[38:39], 0xc00
	v_lshl_add_u64 v[0:1], v[0:1], 0, s[38:39]
	global_load_dwordx4 v[116:119], v[0:1], off nt
	global_load_dwordx4 v[180:183], v[4:5], off nt
	v_lshl_add_u64 v[0:1], v[4:5], 0, s[2:3]
	global_load_dwordx4 v[172:175], v[0:1], off nt
	v_lshl_add_u64 v[0:1], v[4:5], 0, s[34:35]
	global_load_dwordx4 v[164:167], v[0:1], off nt
	v_lshl_add_u64 v[0:1], v[4:5], 0, s[38:39]
	global_load_dwordx4 v[140:143], v[0:1], off nt
	s_mov_b64 s[48:49], 0x400
	s_mov_b64 s[50:51], 0x800
	s_mov_b64 s[52:53], 0xc00
	s_and_saveexec_b64 s[2:3], s[24:25]
	s_cbranch_execz .LBB0_360
	v_cvt_pk_bf16_f32 v0, v48, s0
	v_add_u32_e32 v1, v235, v237
	ds_write_b16 v1, v0 offset:12288
	v_cvt_pk_bf16_f32 v0, v49, s0
	ds_write_b16 v1, v0 offset:12368
	v_cvt_pk_bf16_f32 v0, v50, s0
	ds_write_b16 v1, v0 offset:12448
	v_cvt_pk_bf16_f32 v0, v51, s0
	ds_write_b16 v1, v0 offset:12528
	v_cvt_pk_bf16_f32 v0, v52, s0
	ds_write_b16 v1, v0 offset:12928
	v_cvt_pk_bf16_f32 v0, v53, s0
	ds_write_b16 v1, v0 offset:13008
	v_cvt_pk_bf16_f32 v0, v54, s0
	ds_write_b16 v1, v0 offset:13088
	v_cvt_pk_bf16_f32 v0, v55, s0
	ds_write_b16 v1, v0 offset:13168
	v_cvt_pk_bf16_f32 v0, v56, s0
	ds_write_b16 v1, v0 offset:13568
	v_cvt_pk_bf16_f32 v0, v57, s0
	ds_write_b16 v1, v0 offset:13648
	v_cvt_pk_bf16_f32 v0, v58, s0
	ds_write_b16 v1, v0 offset:13728
	v_cvt_pk_bf16_f32 v0, v59, s0
	ds_write_b16 v1, v0 offset:13808
	v_cvt_pk_bf16_f32 v0, v60, s0
	ds_write_b16 v1, v0 offset:14208
	v_cvt_pk_bf16_f32 v0, v61, s0
	ds_write_b16 v1, v0 offset:14288
	v_cvt_pk_bf16_f32 v0, v62, s0
	ds_write_b16 v1, v0 offset:14368
	v_cvt_pk_bf16_f32 v0, v63, s0
	ds_write_b16 v1, v0 offset:14448
	v_add_u32_e32 v0, v236, v238
	ds_read_b128 v[4:7], v0 offset:12288
	ds_read_b128 v[8:11], v0 offset:13568
	s_waitcnt lgkmcnt(1)
	global_store_dwordx4 v[216:217], v[4:7], off
	s_waitcnt lgkmcnt(0)
	global_store_dwordx4 v[214:215], v[8:11], off
	s_branch .LBB0_360
